# EpiGate1 (T GEMM epilogue): gate vectors of six row groups prefetched at the top of the epilogue instead of eight serialized load/wait/store blocks
# speedup vs baseline: 1.0007x; 1.0007x over previous
; __device__ __forceinline__ unsigned pk2(float lo, float hi) { f32x2 v = {lo, hi}; bf16x2_t b = __builtin_convertvector(v, bf16x2_t); return __builtin_bit_cast(unsigned, b); }
; __device__ __forceinline__ float bflo(unsigned w) { return __uint_as_float(w << 16); }
; __device__ __forceinline__ float bfhi(unsigned w) { return __uint_as_float(w & 0xffff0000u); }
;     __device__ __forceinline__ void operator()(const f32x4 (&acc)[2][2][4][2], const Unit& u, int wr, int wc, int fr, int fq) const {
;         const int col0 = u.pn * 256 + wc * 32 + 8 * fq;
; #pragma unroll
;         for (int ai = 0; ai < 2; ++ai)
; #pragma unroll
;             for (int m = 0; m < 4; ++m) {
;                 const int row = u.pm * 256 + ai * 128 + wr * 64 + m * 16 + fr;
;                 if (row < MR) {
; #pragma unroll
;                     for (int bj = 0; bj < 2; ++bj) {
;                         const u32x4 gv = *(const u32x4*)(GATE + (size_t)row * 2048 + col0 + bj * 128);
;                         f32x4 a = acc[ai][bj][m][0], b = acc[ai][bj][m][1];
;                         a[0] *= bflo(gv.x); a[1] *= bfhi(gv.x); a[2] *= bflo(gv.y); a[3] *= bfhi(gv.y);
;                         b[0] *= bflo(gv.z); b[1] *= bfhi(gv.z); b[2] *= bflo(gv.w); b[3] *= bfhi(gv.w);
;                         u32x4 w; w.x = pk2(a[0], a[1]); w.y = pk2(a[2], a[3]); w.z = pk2(b[0], b[1]); w.w = pk2(b[2], b[3]);
;                         *(u32x4*)(T + (size_t)row * DM + col0 + bj * 128) = w;
;                     }
;                 }
;                 asm volatile("" ::: "memory");
;             }
;     }
.LBB0_1849:
	v_lshl_or_b32 v144, s24, 8, v150
	v_lshl_add_u32 v146, s26, 8, v148
	v_ashrrev_i32_e32 v145, 31, v144
	v_cmp_gt_i32_e32 vcc, s59, v146
	v_lshlrev_b64 v[144:145], 1, v[144:145]
	v_mov_b32_e32 v227, 0
	v_mov_b32_e32 v226, v146
	v_lshlrev_b32_e32 v226, 12, v226
	v_lshl_add_u64 v[228:229], s[10:11], 0, v[226:227]
	v_lshl_add_u64 v[228:229], v[228:229], 0, v[144:145]
	global_load_dwordx4 v[172:175], v[228:229], off
	global_load_dwordx4 v[182:185], v[228:229], off offset:256
	v_add_u32_e32 v226, 0x10, v146
	v_lshlrev_b32_e32 v226, 12, v226
	v_lshl_add_u64 v[228:229], s[10:11], 0, v[226:227]
	v_lshl_add_u64 v[228:229], v[228:229], 0, v[144:145]
	global_load_dwordx4 v[186:189], v[228:229], off
	global_load_dwordx4 v[190:193], v[228:229], off offset:256
	v_add_u32_e32 v226, 0x20, v146
	v_lshlrev_b32_e32 v226, 12, v226
	v_lshl_add_u64 v[228:229], s[10:11], 0, v[226:227]
	v_lshl_add_u64 v[228:229], v[228:229], 0, v[144:145]
	global_load_dwordx4 v[194:197], v[228:229], off
	global_load_dwordx4 v[198:201], v[228:229], off offset:256
	v_add_u32_e32 v226, 0x30, v146
	v_lshlrev_b32_e32 v226, 12, v226
	v_lshl_add_u64 v[228:229], s[10:11], 0, v[226:227]
	v_lshl_add_u64 v[228:229], v[228:229], 0, v[144:145]
	global_load_dwordx4 v[202:205], v[228:229], off
	global_load_dwordx4 v[206:209], v[228:229], off offset:256
	v_add_u32_e32 v226, 0x80, v146
	v_lshlrev_b32_e32 v226, 12, v226
	v_lshl_add_u64 v[228:229], s[10:11], 0, v[226:227]
	v_lshl_add_u64 v[228:229], v[228:229], 0, v[144:145]
	global_load_dwordx4 v[210:213], v[228:229], off
	global_load_dwordx4 v[214:217], v[228:229], off offset:256
	v_add_u32_e32 v226, 0x90, v146
	v_lshlrev_b32_e32 v226, 12, v226
	v_lshl_add_u64 v[228:229], s[10:11], 0, v[226:227]
	v_lshl_add_u64 v[228:229], v[228:229], 0, v[144:145]
	global_load_dwordx4 v[230:233], v[228:229], off
	global_load_dwordx4 v[234:237], v[228:229], off offset:256
	s_and_saveexec_b64 s[24:25], vcc
	s_cbranch_execz .LBB0_1851
	v_ashrrev_i32_e32 v147, 31, v146
	v_lshlrev_b64 v[154:155], 12, v[146:147]
	v_lshl_add_u64 v[154:155], s[10:11], 0, v[154:155]
	v_lshl_add_u64 v[158:159], v[154:155], 0, v[144:145]
	s_waitcnt vmcnt(10)
	v_mov_b32_e32 v154, v172
	v_mov_b32_e32 v155, v173
	v_mov_b32_e32 v156, v174
	v_mov_b32_e32 v157, v175
	v_mov_b32_e32 v158, v182
	v_mov_b32_e32 v159, v183
	v_mov_b32_e32 v160, v184
	v_mov_b32_e32 v161, v185
	v_lshlrev_b64 v[162:163], 11, v[146:147]
	v_lshl_add_u64 v[162:163], s[8:9], 0, v[162:163]
	v_lshl_add_u64 v[162:163], v[162:163], 0, v[144:145]
	v_lshlrev_b32_e32 v164, 16, v154
	v_and_b32_e32 v165, 0xffff0000, v154
	v_lshlrev_b32_e32 v154, 16, v155
	v_and_b32_e32 v155, 0xffff0000, v155
	v_lshlrev_b32_e32 v166, 16, v156
	v_and_b32_e32 v167, 0xffff0000, v156
	v_lshlrev_b32_e32 v156, 16, v157
	v_and_b32_e32 v157, 0xffff0000, v157
	v_lshlrev_b32_e32 v168, 16, v158
	v_and_b32_e32 v169, 0xffff0000, v158
	v_lshlrev_b32_e32 v158, 16, v159
	v_and_b32_e32 v159, 0xffff0000, v159
	v_lshlrev_b32_e32 v170, 16, v160
	v_and_b32_e32 v171, 0xffff0000, v160
	v_lshlrev_b32_e32 v160, 16, v161
	v_and_b32_e32 v161, 0xffff0000, v161
	v_pk_mul_f32 v[124:125], v[124:125], v[164:165]
	v_pk_mul_f32 v[126:127], v[126:127], v[154:155]
	v_pk_mul_f32 v[120:121], v[120:121], v[166:167]
	v_pk_mul_f32 v[122:123], v[122:123], v[156:157]
	v_pk_mul_f32 v[116:117], v[116:117], v[168:169]
	v_pk_mul_f32 v[118:119], v[118:119], v[158:159]
	v_pk_mul_f32 v[154:155], v[112:113], v[170:171]
	v_pk_mul_f32 v[156:157], v[114:115], v[160:161]
	v_cvt_pk_bf16_f32 v112, v124, v125
	v_cvt_pk_bf16_f32 v113, v126, v127
	v_cvt_pk_bf16_f32 v114, v120, v121
	v_cvt_pk_bf16_f32 v115, v122, v123
	v_cvt_pk_bf16_f32 v116, v116, v117
	v_cvt_pk_bf16_f32 v117, v118, v119
	v_cvt_pk_bf16_f32 v118, v154, v155
	v_cvt_pk_bf16_f32 v119, v156, v157
	global_store_dwordx4 v[162:163], v[112:115], off
	global_store_dwordx4 v[162:163], v[116:119], off offset:256
.LBB0_1851:
	s_or_b64 exec, exec, s[24:25]
	v_or_b32_e32 v112, 16, v146
	v_cmp_gt_i32_e32 vcc, s59, v112
	s_and_saveexec_b64 s[24:25], vcc
	s_cbranch_execz .LBB0_1853
	v_ashrrev_i32_e32 v113, 31, v112
	v_lshlrev_b64 v[114:115], 12, v[112:113]
	v_lshl_add_u64 v[114:115], s[10:11], 0, v[114:115]
	v_lshl_add_u64 v[118:119], v[114:115], 0, v[144:145]
	s_waitcnt vmcnt(10)
	v_mov_b32_e32 v114, v186
	v_mov_b32_e32 v115, v187
	v_mov_b32_e32 v116, v188
	v_mov_b32_e32 v117, v189
	v_mov_b32_e32 v118, v190
	v_mov_b32_e32 v119, v191
	v_mov_b32_e32 v120, v192
	v_mov_b32_e32 v121, v193
	v_lshlrev_b64 v[112:113], 11, v[112:113]
	v_lshl_add_u64 v[112:113], s[8:9], 0, v[112:113]
	v_lshl_add_u64 v[112:113], v[112:113], 0, v[144:145]
	v_lshlrev_b32_e32 v122, 16, v114
	v_and_b32_e32 v123, 0xffff0000, v114
	v_lshlrev_b32_e32 v114, 16, v115
	v_and_b32_e32 v115, 0xffff0000, v115
	v_lshlrev_b32_e32 v124, 16, v116
	v_and_b32_e32 v125, 0xffff0000, v116
	v_lshlrev_b32_e32 v116, 16, v117
	v_and_b32_e32 v117, 0xffff0000, v117
	v_lshlrev_b32_e32 v126, 16, v118
	v_and_b32_e32 v127, 0xffff0000, v118
	v_lshlrev_b32_e32 v118, 16, v119
	v_and_b32_e32 v119, 0xffff0000, v119
	v_lshlrev_b32_e32 v154, 16, v120
	v_and_b32_e32 v155, 0xffff0000, v120
	v_lshlrev_b32_e32 v120, 16, v121
	v_and_b32_e32 v121, 0xffff0000, v121
	v_pk_mul_f32 v[108:109], v[108:109], v[122:123]
	v_pk_mul_f32 v[110:111], v[110:111], v[114:115]
	v_pk_mul_f32 v[104:105], v[104:105], v[124:125]
	v_pk_mul_f32 v[106:107], v[106:107], v[116:117]
	v_pk_mul_f32 v[100:101], v[100:101], v[126:127]
	v_pk_mul_f32 v[102:103], v[102:103], v[118:119]
	v_pk_mul_f32 v[114:115], v[96:97], v[154:155]
	v_pk_mul_f32 v[116:117], v[98:99], v[120:121]
	v_cvt_pk_bf16_f32 v96, v108, v109
	v_cvt_pk_bf16_f32 v97, v110, v111
	v_cvt_pk_bf16_f32 v98, v104, v105
	v_cvt_pk_bf16_f32 v99, v106, v107
	v_cvt_pk_bf16_f32 v100, v100, v101
	v_cvt_pk_bf16_f32 v101, v102, v103
	v_cvt_pk_bf16_f32 v102, v114, v115
	v_cvt_pk_bf16_f32 v103, v116, v117
	global_store_dwordx4 v[112:113], v[96:99], off
	global_store_dwordx4 v[112:113], v[100:103], off offset:256
; __device__ __forceinline__ unsigned pk2(float lo, float hi) { f32x2 v = {lo, hi}; bf16x2_t b = __builtin_convertvector(v, bf16x2_t); return __builtin_bit_cast(unsigned, b); }
; __device__ __forceinline__ float bflo(unsigned w) { return __uint_as_float(w << 16); }
; __device__ __forceinline__ float bfhi(unsigned w) { return __uint_as_float(w & 0xffff0000u); }
;     __device__ __forceinline__ void operator()(const f32x4 (&acc)[2][2][4][2], const Unit& u, int wr, int wc, int fr, int fq) const {
;     ...
;             for (int m = 0; m < 4; ++m) {
;                 const int row = u.pm * 256 + ai * 128 + wr * 64 + m * 16 + fr;
;                 if (row < MR) {
; #pragma unroll
;                     for (int bj = 0; bj < 2; ++bj) {
;                         const u32x4 gv = *(const u32x4*)(GATE + (size_t)row * 2048 + col0 + bj * 128);
;                         f32x4 a = acc[ai][bj][m][0], b = acc[ai][bj][m][1];
;                         a[0] *= bflo(gv.x); a[1] *= bfhi(gv.x); a[2] *= bflo(gv.y); a[3] *= bfhi(gv.y);
;                         b[0] *= bflo(gv.z); b[1] *= bfhi(gv.z); b[2] *= bflo(gv.w); b[3] *= bfhi(gv.w);
;                         u32x4 w; w.x = pk2(a[0], a[1]); w.y = pk2(a[2], a[3]); w.z = pk2(b[0], b[1]); w.w = pk2(b[2], b[3]);
;                         *(u32x4*)(T + (size_t)row * DM + col0 + bj * 128) = w;
;                     }
;                 }
.LBB0_1853:
	s_or_b64 exec, exec, s[24:25]
	v_or_b32_e32 v96, 32, v146
	v_cmp_gt_i32_e32 vcc, s59, v96
	s_and_saveexec_b64 s[24:25], vcc
	s_cbranch_execz .LBB0_1855
	v_ashrrev_i32_e32 v97, 31, v96
	v_lshlrev_b64 v[98:99], 12, v[96:97]
	v_lshl_add_u64 v[98:99], s[10:11], 0, v[98:99]
	v_lshl_add_u64 v[102:103], v[98:99], 0, v[144:145]
	s_waitcnt vmcnt(10)
	v_mov_b32_e32 v98, v194
	v_mov_b32_e32 v99, v195
	v_mov_b32_e32 v100, v196
	v_mov_b32_e32 v101, v197
	v_mov_b32_e32 v102, v198
	v_mov_b32_e32 v103, v199
	v_mov_b32_e32 v104, v200
	v_mov_b32_e32 v105, v201
	v_lshlrev_b64 v[96:97], 11, v[96:97]
	v_lshl_add_u64 v[96:97], s[8:9], 0, v[96:97]
	v_lshl_add_u64 v[96:97], v[96:97], 0, v[144:145]
	v_lshlrev_b32_e32 v106, 16, v98
	v_and_b32_e32 v107, 0xffff0000, v98
	v_lshlrev_b32_e32 v98, 16, v99
	v_and_b32_e32 v99, 0xffff0000, v99
	v_lshlrev_b32_e32 v108, 16, v100
	v_and_b32_e32 v109, 0xffff0000, v100
	v_lshlrev_b32_e32 v100, 16, v101
	v_and_b32_e32 v101, 0xffff0000, v101
	v_lshlrev_b32_e32 v110, 16, v102
	v_and_b32_e32 v111, 0xffff0000, v102
	v_lshlrev_b32_e32 v102, 16, v103
	v_and_b32_e32 v103, 0xffff0000, v103
	v_lshlrev_b32_e32 v112, 16, v104
	v_and_b32_e32 v113, 0xffff0000, v104
	v_lshlrev_b32_e32 v104, 16, v105
	v_and_b32_e32 v105, 0xffff0000, v105
	v_pk_mul_f32 v[92:93], v[92:93], v[106:107]
	v_pk_mul_f32 v[94:95], v[94:95], v[98:99]
	v_pk_mul_f32 v[88:89], v[88:89], v[108:109]
	v_pk_mul_f32 v[90:91], v[90:91], v[100:101]
	v_pk_mul_f32 v[84:85], v[84:85], v[110:111]
	v_pk_mul_f32 v[86:87], v[86:87], v[102:103]
	v_pk_mul_f32 v[98:99], v[80:81], v[112:113]
	v_pk_mul_f32 v[100:101], v[82:83], v[104:105]
	v_cvt_pk_bf16_f32 v80, v92, v93
	v_cvt_pk_bf16_f32 v81, v94, v95
	v_cvt_pk_bf16_f32 v82, v88, v89
	v_cvt_pk_bf16_f32 v83, v90, v91
	v_cvt_pk_bf16_f32 v84, v84, v85
	v_cvt_pk_bf16_f32 v85, v86, v87
	v_cvt_pk_bf16_f32 v86, v98, v99
	v_cvt_pk_bf16_f32 v87, v100, v101
	global_store_dwordx4 v[96:97], v[80:83], off
	global_store_dwordx4 v[96:97], v[84:87], off offset:256
.LBB0_1855:
	s_or_b64 exec, exec, s[24:25]
	v_or_b32_e32 v80, 48, v146
	v_cmp_gt_i32_e32 vcc, s59, v80
	s_and_saveexec_b64 s[24:25], vcc
	s_cbranch_execz .LBB0_1857
	v_ashrrev_i32_e32 v81, 31, v80
	v_lshlrev_b64 v[82:83], 12, v[80:81]
	v_lshl_add_u64 v[82:83], s[10:11], 0, v[82:83]
	v_lshl_add_u64 v[86:87], v[82:83], 0, v[144:145]
	s_waitcnt vmcnt(10)
	v_mov_b32_e32 v82, v202
	v_mov_b32_e32 v83, v203
	v_mov_b32_e32 v84, v204
	v_mov_b32_e32 v85, v205
	v_mov_b32_e32 v86, v206
	v_mov_b32_e32 v87, v207
	v_mov_b32_e32 v88, v208
	v_mov_b32_e32 v89, v209
	v_lshlrev_b64 v[80:81], 11, v[80:81]
	v_lshl_add_u64 v[80:81], s[8:9], 0, v[80:81]
	v_lshl_add_u64 v[80:81], v[80:81], 0, v[144:145]
	v_lshlrev_b32_e32 v90, 16, v82
	v_and_b32_e32 v91, 0xffff0000, v82
	v_lshlrev_b32_e32 v82, 16, v83
	v_and_b32_e32 v83, 0xffff0000, v83
	v_lshlrev_b32_e32 v92, 16, v84
	v_and_b32_e32 v93, 0xffff0000, v84
	v_lshlrev_b32_e32 v84, 16, v85
	v_and_b32_e32 v85, 0xffff0000, v85
	v_lshlrev_b32_e32 v94, 16, v86
	v_and_b32_e32 v95, 0xffff0000, v86
	v_lshlrev_b32_e32 v86, 16, v87
	v_and_b32_e32 v87, 0xffff0000, v87
	v_lshlrev_b32_e32 v96, 16, v88
	v_and_b32_e32 v97, 0xffff0000, v88
	v_lshlrev_b32_e32 v88, 16, v89
	v_and_b32_e32 v89, 0xffff0000, v89
	v_pk_mul_f32 v[76:77], v[76:77], v[90:91]
	v_pk_mul_f32 v[78:79], v[78:79], v[82:83]
	v_pk_mul_f32 v[72:73], v[72:73], v[92:93]
	v_pk_mul_f32 v[74:75], v[74:75], v[84:85]
	v_pk_mul_f32 v[68:69], v[68:69], v[94:95]
	v_pk_mul_f32 v[70:71], v[70:71], v[86:87]
	v_pk_mul_f32 v[82:83], v[64:65], v[96:97]
	v_pk_mul_f32 v[84:85], v[66:67], v[88:89]
	v_cvt_pk_bf16_f32 v64, v76, v77
	v_cvt_pk_bf16_f32 v65, v78, v79
	v_cvt_pk_bf16_f32 v66, v72, v73
	v_cvt_pk_bf16_f32 v67, v74, v75
	v_cvt_pk_bf16_f32 v68, v68, v69
	v_cvt_pk_bf16_f32 v69, v70, v71
	v_cvt_pk_bf16_f32 v70, v82, v83
	v_cvt_pk_bf16_f32 v71, v84, v85
	global_store_dwordx4 v[80:81], v[64:67], off
	global_store_dwordx4 v[80:81], v[68:71], off offset:256
; __device__ __forceinline__ unsigned pk2(float lo, float hi) { f32x2 v = {lo, hi}; bf16x2_t b = __builtin_convertvector(v, bf16x2_t); return __builtin_bit_cast(unsigned, b); }
; __device__ __forceinline__ float bflo(unsigned w) { return __uint_as_float(w << 16); }
; __device__ __forceinline__ float bfhi(unsigned w) { return __uint_as_float(w & 0xffff0000u); }
;     __device__ __forceinline__ void operator()(const f32x4 (&acc)[2][2][4][2], const Unit& u, int wr, int wc, int fr, int fq) const {
;     ...
;             for (int m = 0; m < 4; ++m) {
;                 const int row = u.pm * 256 + ai * 128 + wr * 64 + m * 16 + fr;
;                 if (row < MR) {
; #pragma unroll
;                     for (int bj = 0; bj < 2; ++bj) {
;                         const u32x4 gv = *(const u32x4*)(GATE + (size_t)row * 2048 + col0 + bj * 128);
;                         f32x4 a = acc[ai][bj][m][0], b = acc[ai][bj][m][1];
;                         a[0] *= bflo(gv.x); a[1] *= bfhi(gv.x); a[2] *= bflo(gv.y); a[3] *= bfhi(gv.y);
;                         b[0] *= bflo(gv.z); b[1] *= bfhi(gv.z); b[2] *= bflo(gv.w); b[3] *= bfhi(gv.w);
;                         u32x4 w; w.x = pk2(a[0], a[1]); w.y = pk2(a[2], a[3]); w.z = pk2(b[0], b[1]); w.w = pk2(b[2], b[3]);
;                         *(u32x4*)(T + (size_t)row * DM + col0 + bj * 128) = w;
;                     }
;                 }
.LBB0_1857:
	s_or_b64 exec, exec, s[24:25]
	v_add_u32_e32 v64, 0x80, v146
	v_cmp_gt_i32_e32 vcc, s59, v64
	s_and_saveexec_b64 s[24:25], vcc
	s_cbranch_execz .LBB0_1859
	v_ashrrev_i32_e32 v65, 31, v64
	v_lshlrev_b64 v[66:67], 12, v[64:65]
	v_lshl_add_u64 v[66:67], s[10:11], 0, v[66:67]
	v_lshl_add_u64 v[70:71], v[66:67], 0, v[144:145]
	s_waitcnt vmcnt(10)
	v_mov_b32_e32 v66, v210
	v_mov_b32_e32 v67, v211
	v_mov_b32_e32 v68, v212
	v_mov_b32_e32 v69, v213
	v_mov_b32_e32 v70, v214
	v_mov_b32_e32 v71, v215
	v_mov_b32_e32 v72, v216
	v_mov_b32_e32 v73, v217
	v_lshlrev_b64 v[64:65], 11, v[64:65]
	v_lshl_add_u64 v[64:65], s[8:9], 0, v[64:65]
	v_lshl_add_u64 v[64:65], v[64:65], 0, v[144:145]
	v_lshlrev_b32_e32 v74, 16, v66
	v_and_b32_e32 v75, 0xffff0000, v66
	v_lshlrev_b32_e32 v66, 16, v67
	v_and_b32_e32 v67, 0xffff0000, v67
	v_lshlrev_b32_e32 v76, 16, v68
	v_and_b32_e32 v77, 0xffff0000, v68
	v_lshlrev_b32_e32 v68, 16, v69
	v_and_b32_e32 v69, 0xffff0000, v69
	v_lshlrev_b32_e32 v78, 16, v70
	v_and_b32_e32 v79, 0xffff0000, v70
	v_lshlrev_b32_e32 v70, 16, v71
	v_and_b32_e32 v71, 0xffff0000, v71
	v_lshlrev_b32_e32 v80, 16, v72
	v_and_b32_e32 v81, 0xffff0000, v72
	v_lshlrev_b32_e32 v72, 16, v73
	v_and_b32_e32 v73, 0xffff0000, v73
	v_pk_mul_f32 v[60:61], v[60:61], v[74:75]
	v_pk_mul_f32 v[62:63], v[62:63], v[66:67]
	v_pk_mul_f32 v[56:57], v[56:57], v[76:77]
	v_pk_mul_f32 v[58:59], v[58:59], v[68:69]
	v_pk_mul_f32 v[52:53], v[52:53], v[78:79]
	v_pk_mul_f32 v[54:55], v[54:55], v[70:71]
	v_pk_mul_f32 v[66:67], v[48:49], v[80:81]
	v_pk_mul_f32 v[68:69], v[50:51], v[72:73]
	v_cvt_pk_bf16_f32 v48, v60, v61
	v_cvt_pk_bf16_f32 v49, v62, v63
	v_cvt_pk_bf16_f32 v50, v56, v57
	v_cvt_pk_bf16_f32 v51, v58, v59
	v_cvt_pk_bf16_f32 v52, v52, v53
	v_cvt_pk_bf16_f32 v53, v54, v55
	v_cvt_pk_bf16_f32 v54, v66, v67
	v_cvt_pk_bf16_f32 v55, v68, v69
	global_store_dwordx4 v[64:65], v[48:51], off
	global_store_dwordx4 v[64:65], v[52:55], off offset:256
.LBB0_1859:
	s_or_b64 exec, exec, s[24:25]
	v_add_u32_e32 v48, 0x90, v146
	v_cmp_gt_i32_e32 vcc, s59, v48
	s_and_saveexec_b64 s[24:25], vcc
	s_cbranch_execz .LBB0_1861
	v_ashrrev_i32_e32 v49, 31, v48
	v_lshlrev_b64 v[50:51], 12, v[48:49]
	v_lshl_add_u64 v[50:51], s[10:11], 0, v[50:51]
	v_lshl_add_u64 v[54:55], v[50:51], 0, v[144:145]
	s_waitcnt vmcnt(10)
	v_mov_b32_e32 v50, v230
	v_mov_b32_e32 v51, v231
	v_mov_b32_e32 v52, v232
	v_mov_b32_e32 v53, v233
	v_mov_b32_e32 v54, v234
	v_mov_b32_e32 v55, v235
	v_mov_b32_e32 v56, v236
	v_mov_b32_e32 v57, v237
	v_lshlrev_b64 v[48:49], 11, v[48:49]
	v_lshl_add_u64 v[48:49], s[8:9], 0, v[48:49]
	v_lshl_add_u64 v[48:49], v[48:49], 0, v[144:145]
	v_lshlrev_b32_e32 v58, 16, v50
	v_and_b32_e32 v59, 0xffff0000, v50
	v_lshlrev_b32_e32 v50, 16, v51
	v_and_b32_e32 v51, 0xffff0000, v51
	v_lshlrev_b32_e32 v60, 16, v52
	v_and_b32_e32 v61, 0xffff0000, v52
	v_lshlrev_b32_e32 v52, 16, v53
	v_and_b32_e32 v53, 0xffff0000, v53
	v_lshlrev_b32_e32 v62, 16, v54
	v_and_b32_e32 v63, 0xffff0000, v54
	v_lshlrev_b32_e32 v54, 16, v55
	v_and_b32_e32 v55, 0xffff0000, v55
	v_lshlrev_b32_e32 v64, 16, v56
	v_and_b32_e32 v65, 0xffff0000, v56
	v_lshlrev_b32_e32 v56, 16, v57
	v_and_b32_e32 v57, 0xffff0000, v57
	v_pk_mul_f32 v[44:45], v[44:45], v[58:59]
	v_pk_mul_f32 v[46:47], v[46:47], v[50:51]
	v_pk_mul_f32 v[40:41], v[40:41], v[60:61]
	v_pk_mul_f32 v[42:43], v[42:43], v[52:53]
	v_pk_mul_f32 v[36:37], v[36:37], v[62:63]
	v_pk_mul_f32 v[38:39], v[38:39], v[54:55]
	v_pk_mul_f32 v[50:51], v[32:33], v[64:65]
	v_pk_mul_f32 v[52:53], v[34:35], v[56:57]
	v_cvt_pk_bf16_f32 v32, v44, v45
	v_cvt_pk_bf16_f32 v33, v46, v47
	v_cvt_pk_bf16_f32 v34, v40, v41
	v_cvt_pk_bf16_f32 v35, v42, v43
	v_cvt_pk_bf16_f32 v36, v36, v37
	v_cvt_pk_bf16_f32 v37, v38, v39
	v_cvt_pk_bf16_f32 v38, v50, v51
	v_cvt_pk_bf16_f32 v39, v52, v53
	global_store_dwordx4 v[48:49], v[32:35], off
	global_store_dwordx4 v[48:49], v[36:39], off offset:256
